# waiting workgroups poll the arrival counters directly (per-XCC arrival count for XCD-local rounds, cross-XCC generation for device-wide rounds)
# baseline (speedup 1.0000x reference)
; __device__ __forceinline__ unsigned xb_add(unsigned* p, unsigned v) { return __hip_atomic_fetch_add(p, v, __ATOMIC_RELAXED, __HIP_MEMORY_SCOPE_AGENT); }
; __device__ __forceinline__ void xcd_barrier(const XcdBarrier& b) {
;     asm volatile("s_waitcnt vmcnt(0)" ::: "memory");
;     __syncthreads();
;     if (threadIdx.x == 0) {
;         unsigned* bar = b.bar;
;         __builtin_amdgcn_s_waitcnt(0);
;         unsigned nloc = b.st[0], nx = b.st[1];
;         if (nloc == 0u) { xcd_barrier_complete(bar, b.x, nloc, nx); b.st[0] = nloc; b.st[1] = nx; }
;         const unsigned old = xb_add(&bar[XB_XSUB(b.x)], 1u);
.LBB0_357:
	v_readlane_b32 s2, v255, 28
	v_readlane_b32 s3, v255, 29
	s_xor_b64 s[6:7], s[2:3], -1
	v_writelane_b32 v255, s6, 48
	s_mov_b64 s[2:3], -1
	s_and_b64 vcc, exec, s[6:7]
	v_writelane_b32 v255, s7, 49
	s_cbranch_vccz .LBB0_413
	v_readlane_b32 s2, v252, 17
	v_readlane_b32 s3, v252, 18
	s_andn2_b64 vcc, exec, s[2:3]
	s_cbranch_vccnz .LBB0_412
	s_waitcnt vmcnt(0)
	s_barrier
	s_mov_b64 s[2:3], exec
	v_readlane_b32 s6, v252, 10
	v_readlane_b32 s7, v252, 11
	s_and_b64 s[6:7], s[2:3], s[6:7]
	s_mov_b64 exec, s[6:7]
	s_cbranch_execz .LBB0_411
	v_mov_b32_e32 v4, 0x26a48
	ds_read_b32 v5, v4
	s_waitcnt lgkmcnt(0)
	v_add_u32_e32 v5, 1, v5
	ds_write_b32 v4, v5
	v_readlane_b32 s1, v255, 21
	s_waitcnt vmcnt(0) expcnt(0) lgkmcnt(0)
	s_nop 0
	v_mov_b32_e32 v1, s1
	ds_read_b32 v3, v1
	v_readlane_b32 s1, v255, 22
	s_waitcnt lgkmcnt(0)
	v_cmp_ne_u32_e32 vcc, 0, v3
	v_mov_b32_e32 v1, s1
	ds_read_b32 v1, v1
	s_cbranch_vccnz .LBB0_375
	s_mov_b32 s4, 1
	s_branch .LBB0_363

; __device__ __forceinline__ unsigned xb_add(unsigned* p, unsigned v) { return __hip_atomic_fetch_add(p, v, __ATOMIC_RELAXED, __HIP_MEMORY_SCOPE_AGENT); }
; __device__ __forceinline__ void xcd_barrier(const XcdBarrier& b) {
;     asm volatile("s_waitcnt vmcnt(0)" ::: "memory");
;     __syncthreads();
;     if (threadIdx.x == 0) {
;         unsigned* bar = b.bar;
;         __builtin_amdgcn_s_waitcnt(0);
;         unsigned nloc = b.st[0], nx = b.st[1];
;         if (nloc == 0u) { xcd_barrier_complete(bar, b.x, nloc, nx); b.st[0] = nloc; b.st[1] = nx; }
;         const unsigned old = xb_add(&bar[XB_XSUB(b.x)], 1u);
.LBB0_426:
	s_waitcnt vmcnt(0)
	s_barrier
	s_mov_b64 s[2:3], exec
	v_readlane_b32 s6, v252, 10
	v_readlane_b32 s7, v252, 11
	s_and_b64 s[6:7], s[2:3], s[6:7]
	s_mov_b64 exec, s[6:7]
	s_cbranch_execz .LBB0_478
	v_mov_b32_e32 v4, 0x26a48
	ds_read_b32 v5, v4
	s_waitcnt lgkmcnt(0)
	v_add_u32_e32 v5, 1, v5
	ds_write_b32 v4, v5
	v_readlane_b32 s1, v255, 21
	s_waitcnt vmcnt(0) expcnt(0) lgkmcnt(0)
	s_nop 0
	v_mov_b32_e32 v1, s1
	ds_read_b32 v3, v1
	v_readlane_b32 s1, v255, 22
	s_waitcnt lgkmcnt(0)
	v_cmp_ne_u32_e32 vcc, 0, v3
	v_mov_b32_e32 v1, s1
	ds_read_b32 v1, v1
	s_cbranch_vccnz .LBB0_442
	s_mov_b32 s4, 1
	s_branch .LBB0_430

; __device__ __forceinline__ unsigned xb_add(unsigned* p, unsigned v) { return __hip_atomic_fetch_add(p, v, __ATOMIC_RELAXED, __HIP_MEMORY_SCOPE_AGENT); }
; __device__ __forceinline__ void xcd_barrier(const XcdBarrier& b) {
;     asm volatile("s_waitcnt vmcnt(0)" ::: "memory");
;     __syncthreads();
;     if (threadIdx.x == 0) {
;         unsigned* bar = b.bar;
;         __builtin_amdgcn_s_waitcnt(0);
;         unsigned nloc = b.st[0], nx = b.st[1];
;         if (nloc == 0u) { xcd_barrier_complete(bar, b.x, nloc, nx); b.st[0] = nloc; b.st[1] = nx; }
;         const unsigned old = xb_add(&bar[XB_XSUB(b.x)], 1u);
.LBB0_808:
	s_waitcnt vmcnt(0)
	s_waitcnt vmcnt(0) lgkmcnt(0)
	s_barrier
	s_mov_b64 s[2:3], exec
	v_readlane_b32 s6, v252, 10
	v_readlane_b32 s7, v252, 11
	s_and_b64 s[6:7], s[2:3], s[6:7]
	s_mov_b64 exec, s[6:7]
	s_cbranch_execz .LBB0_860
	v_mov_b32_e32 v4, 0x26a38
	ds_read_b32 v5, v4
	ds_read_b32 v6, v4 offset:16
	s_waitcnt lgkmcnt(0)
	v_cmp_eq_u32_e32 vcc, 0, v5
	s_nop 1
	v_cndmask_b32_e64 v5, 0, 1, vcc
	v_add_u32_e32 v6, v6, v5
	ds_write_b32 v4, v6 offset:16
	v_readlane_b32 s1, v255, 21
	s_waitcnt vmcnt(0) expcnt(0) lgkmcnt(0)
	s_nop 0
	v_mov_b32_e32 v1, s1
	ds_read_b32 v3, v1
	v_readlane_b32 s1, v255, 22
	s_waitcnt lgkmcnt(0)
	v_cmp_ne_u32_e32 vcc, 0, v3
	v_mov_b32_e32 v1, s1
	ds_read_b32 v2, v1
	s_cbranch_vccnz .LBB0_824
	s_mov_b32 s4, 1
	s_branch .LBB0_812

; __device__ __forceinline__ unsigned xb_ld(unsigned* p)              { return __hip_atomic_load(p, __ATOMIC_RELAXED, __HIP_MEMORY_SCOPE_AGENT); }
; __device__ __forceinline__ unsigned xb_add(unsigned* p, unsigned v) { return __hip_atomic_fetch_add(p, v, __ATOMIC_RELAXED, __HIP_MEMORY_SCOPE_AGENT); }
; #define XB_SPIN(cond, bar) do { unsigned _sp = 0; while (cond) { __builtin_amdgcn_s_sleep(1); \
;     if ((++_sp & 255u) == 0u) { if (xb_ld(&(bar)[XB_TMO])) break; if (_sp > XB_SPIN_CAP) { atomicAdd(&(bar)[XB_TMO], 1u); break; } } } } while (0)
; __device__ __forceinline__ void xcd_barrier(const XcdBarrier& b) {
;     ...
;         const unsigned old = xb_add(&bar[XB_XSUB(b.x)], 1u);
;         const unsigned gen = old / nloc;
;         if (old + 1u == (gen + 1u) * nloc) {
;             __builtin_amdgcn_fence(__ATOMIC_RELEASE, "agent");
;             asm volatile("s_waitcnt vmcnt(0)" ::: "memory");
;             const unsigned og = xb_add(&bar[XB_TOP], 1u);
;             const unsigned tg = og / nx;
;             if (og + 1u == (tg + 1u) * nx) xb_add(&bar[XB_TOPGEN], 1u);
;             else XB_SPIN(xb_ld(&bar[XB_TOPGEN]) == tg, bar);
;             __builtin_amdgcn_fence(__ATOMIC_ACQUIRE, "agent");
;             xb_add(&bar[XB_XGEN(b.x)], 1u);
;             asm volatile("s_waitcnt vmcnt(0)" ::: "memory");
;         } else {
;             XB_SPIN(xb_ld(&bar[XB_XGEN(b.x)]) == gen, bar);
;             __builtin_amdgcn_fence(__ATOMIC_ACQUIRE, "agent");
;             asm volatile("s_waitcnt vmcnt(0)" ::: "memory");
.LBB0_826:
	s_or_b64 exec, exec, s[6:7]
	v_cvt_f32_u32_e32 v5, v3
	s_waitcnt vmcnt(0)
	v_readfirstlane_b32 s4, v4
	v_sub_u32_e32 v4, 0, v3
	v_rcp_iflag_f32_e32 v5, v5
	v_add_u32_e32 v6, s4, v1
	v_mul_f32_e32 v5, 0x4f7ffffe, v5
	v_cvt_u32_f32_e32 v5, v5
	v_mul_lo_u32 v1, v4, v5
	v_mul_hi_u32 v1, v5, v1
	v_add_u32_e32 v1, v5, v1
	v_mul_hi_u32 v1, v6, v1
	v_mul_lo_u32 v4, v1, v3
	v_sub_u32_e32 v4, v6, v4
	v_add_u32_e32 v5, 1, v1
	v_cmp_ge_u32_e32 vcc, v4, v3
	s_nop 1
	v_cndmask_b32_e32 v1, v1, v5, vcc
	v_sub_u32_e32 v5, v4, v3
	v_cndmask_b32_e32 v4, v4, v5, vcc
	v_add_u32_e32 v5, 1, v1
	v_cmp_ge_u32_e32 vcc, v4, v3
	v_add_u32_e32 v4, 1, v6
	s_nop 0
	v_cndmask_b32_e32 v1, v1, v5, vcc
	v_mul_lo_u32 v5, v3, v1
	v_add_u32_e32 v3, v5, v3
	v_cmp_ne_u32_e32 vcc, v4, v3
	s_and_saveexec_b64 s[6:7], vcc
	s_xor_b64 s[6:7], exec, s[6:7]
	s_cbranch_execz .LBB0_840
	buffer_inv sc1
	v_mov_b32_e32 v4, 0x26a38
	ds_read_b32 v4, v4
	s_waitcnt lgkmcnt(0)
	v_cmp_ne_u32_e32 vcc, 0, v4
	s_cbranch_vccz .Lnl_full_3
	v_readlane_b32 s8, v253, 34
	v_readlane_b32 s9, v253, 35
	s_mov_b32 s4, 0
	s_nop 3
.Lnl_lspin_3:
	global_load_dword v2, v99, s[8:9] sc1
	s_waitcnt vmcnt(0)
	v_cmp_lt_u32_e32 vcc, v2, v3
	s_cbranch_vccz .Lnl_acq_3
	s_sleep 1
	s_add_i32 s4, s4, 1
	s_cmp_lt_u32 s4, 0x40000
	s_cbranch_scc1 .Lnl_lspin_3
	s_branch .Lnl_acq_3
.Lnl_full_3:
	v_mov_b32_e32 v4, 0x26a48
	ds_read_b32 v4, v4
	v_readlane_b32 s8, v253, 40
	v_readlane_b32 s9, v253, 41
	s_mov_b32 s4, 0
	s_waitcnt lgkmcnt(0)
	s_nop 2
.Lnl_fspin_3:
	global_load_dword v2, v99, s[8:9] sc1
	s_waitcnt vmcnt(0)
	v_cmp_lt_u32_e32 vcc, v2, v4
	s_cbranch_vccz .Lnl_acq_3
	s_sleep 1
	s_add_i32 s4, s4, 1
	s_cmp_lt_u32 s4, 0x40000
	s_cbranch_scc1 .Lnl_fspin_3
	s_branch .Lnl_acq_3
	v_readlane_b32 s8, v253, 36
	v_readlane_b32 s9, v253, 37
	s_waitcnt lgkmcnt(0)
	s_nop 3
	global_load_dword v2, v99, s[8:9] sc1
	s_waitcnt vmcnt(0)
	v_cmp_eq_u32_e32 vcc, v2, v1
	s_and_saveexec_b64 s[8:9], vcc
	s_cbranch_execz .LBB0_839
	s_mov_b32 s4, 1
	s_mov_b64 s[10:11], 0
	s_branch .LBB0_830

; __device__ __forceinline__ unsigned xb_ld(unsigned* p)              { return __hip_atomic_load(p, __ATOMIC_RELAXED, __HIP_MEMORY_SCOPE_AGENT); }
; #define XB_SPIN(cond, bar) do { unsigned _sp = 0; while (cond) { __builtin_amdgcn_s_sleep(1); \
;     if ((++_sp & 255u) == 0u) { if (xb_ld(&(bar)[XB_TMO])) break; if (_sp > XB_SPIN_CAP) { atomicAdd(&(bar)[XB_TMO], 1u); break; } } } } while (0)
; __device__ __forceinline__ void xcd_barrier(const XcdBarrier& b) {
;     ...
;         } else {
;             XB_SPIN(xb_ld(&bar[XB_XGEN(b.x)]) == gen, bar);
;             __builtin_amdgcn_fence(__ATOMIC_ACQUIRE, "agent");
;             asm volatile("s_waitcnt vmcnt(0)" ::: "memory");
.Lnl_acq_3:
	s_waitcnt vmcnt(0)
	s_waitcnt vmcnt(0)

; __device__ __forceinline__ unsigned xb_add(unsigned* p, unsigned v) { return __hip_atomic_fetch_add(p, v, __ATOMIC_RELAXED, __HIP_MEMORY_SCOPE_AGENT); }
; __device__ __forceinline__ void xcd_barrier(const XcdBarrier& b) {
;     asm volatile("s_waitcnt vmcnt(0)" ::: "memory");
;     __syncthreads();
;     if (threadIdx.x == 0) {
;         unsigned* bar = b.bar;
;         __builtin_amdgcn_s_waitcnt(0);
;         unsigned nloc = b.st[0], nx = b.st[1];
;         if (nloc == 0u) { xcd_barrier_complete(bar, b.x, nloc, nx); b.st[0] = nloc; b.st[1] = nx; }
;         const unsigned old = xb_add(&bar[XB_XSUB(b.x)], 1u);
.LBB0_899:
	s_waitcnt vmcnt(0)
	s_waitcnt lgkmcnt(0)
	s_barrier
	s_mov_b64 s[2:3], exec
	v_readlane_b32 s6, v252, 10
	v_readlane_b32 s7, v252, 11
	s_and_b64 s[6:7], s[2:3], s[6:7]
	s_mov_b64 exec, s[6:7]
	s_cbranch_execz .LBB0_951
	v_mov_b32_e32 v4, 0x26a38
	ds_read_b32 v5, v4
	ds_read_b32 v6, v4 offset:16
	s_waitcnt lgkmcnt(0)
	v_cmp_eq_u32_e32 vcc, 0, v5
	s_nop 1
	v_cndmask_b32_e64 v5, 0, 1, vcc
	v_add_u32_e32 v6, v6, v5
	ds_write_b32 v4, v6 offset:16
	v_mov_b32_e32 v4, 0x26a24
	ds_read_b32 v5, v4
	ds_read_b32 v6, v4 offset:28
	s_waitcnt lgkmcnt(0)
	v_add_u32_e32 v5, v6, v5
	ds_write_b32 v4, v5 offset:28
	v_readlane_b32 s1, v255, 21
	s_waitcnt vmcnt(0) expcnt(0) lgkmcnt(0)
	s_nop 0
	v_mov_b32_e32 v1, s1
	ds_read_b32 v3, v1
	v_readlane_b32 s1, v255, 22
	s_waitcnt lgkmcnt(0)
	v_cmp_ne_u32_e32 vcc, 0, v3
	v_mov_b32_e32 v1, s1
	ds_read_b32 v2, v1
	s_cbranch_vccnz .LBB0_915
	s_mov_b32 s4, 1
	s_branch .LBB0_903

; __device__ __forceinline__ unsigned xb_add(unsigned* p, unsigned v) { return __hip_atomic_fetch_add(p, v, __ATOMIC_RELAXED, __HIP_MEMORY_SCOPE_AGENT); }
; __device__ __forceinline__ void xcd_barrier(const XcdBarrier& b) {
;     asm volatile("s_waitcnt vmcnt(0)" ::: "memory");
;     __syncthreads();
;     if (threadIdx.x == 0) {
;         unsigned* bar = b.bar;
;         __builtin_amdgcn_s_waitcnt(0);
;         unsigned nloc = b.st[0], nx = b.st[1];
;         if (nloc == 0u) { xcd_barrier_complete(bar, b.x, nloc, nx); b.st[0] = nloc; b.st[1] = nx; }
;         const unsigned old = xb_add(&bar[XB_XSUB(b.x)], 1u);
.LBB0_1059:
	s_waitcnt vmcnt(0)
	s_waitcnt lgkmcnt(0)
	s_barrier
	s_mov_b64 s[2:3], exec
	v_readlane_b32 s10, v252, 10
	v_readlane_b32 s11, v252, 11
	s_and_b64 s[10:11], s[2:3], s[10:11]
	s_mov_b64 exec, s[10:11]
	s_cbranch_execz .LBB0_1111
	v_mov_b32_e32 v4, 0x26a38
	ds_read_b32 v5, v4
	ds_read_b32 v6, v4 offset:16
	s_waitcnt lgkmcnt(0)
	v_cmp_eq_u32_e32 vcc, 0, v5
	s_nop 1
	v_cndmask_b32_e64 v5, 0, 1, vcc
	v_add_u32_e32 v6, v6, v5
	ds_write_b32 v4, v6 offset:16
	v_readlane_b32 s1, v255, 21
	s_waitcnt vmcnt(0) expcnt(0) lgkmcnt(0)
	s_nop 0
	v_mov_b32_e32 v1, s1
	ds_read_b32 v3, v1
	v_readlane_b32 s1, v255, 22
	s_waitcnt lgkmcnt(0)
	v_cmp_ne_u32_e32 vcc, 0, v3
	v_mov_b32_e32 v1, s1
	ds_read_b32 v2, v1
	s_cbranch_vccnz .LBB0_1075
	s_mov_b32 s4, 1
	s_branch .LBB0_1063

; __device__ __forceinline__ unsigned xb_ld(unsigned* p)              { return __hip_atomic_load(p, __ATOMIC_RELAXED, __HIP_MEMORY_SCOPE_AGENT); }
; __device__ __forceinline__ unsigned xb_add(unsigned* p, unsigned v) { return __hip_atomic_fetch_add(p, v, __ATOMIC_RELAXED, __HIP_MEMORY_SCOPE_AGENT); }
; #define XB_SPIN(cond, bar) do { unsigned _sp = 0; while (cond) { __builtin_amdgcn_s_sleep(1); \
;     if ((++_sp & 255u) == 0u) { if (xb_ld(&(bar)[XB_TMO])) break; if (_sp > XB_SPIN_CAP) { atomicAdd(&(bar)[XB_TMO], 1u); break; } } } } while (0)
; __device__ __forceinline__ void xcd_barrier(const XcdBarrier& b) {
;     ...
;         const unsigned old = xb_add(&bar[XB_XSUB(b.x)], 1u);
;         const unsigned gen = old / nloc;
;         if (old + 1u == (gen + 1u) * nloc) {
;             __builtin_amdgcn_fence(__ATOMIC_RELEASE, "agent");
;             asm volatile("s_waitcnt vmcnt(0)" ::: "memory");
;             const unsigned og = xb_add(&bar[XB_TOP], 1u);
;             const unsigned tg = og / nx;
;             if (og + 1u == (tg + 1u) * nx) xb_add(&bar[XB_TOPGEN], 1u);
;             else XB_SPIN(xb_ld(&bar[XB_TOPGEN]) == tg, bar);
;             __builtin_amdgcn_fence(__ATOMIC_ACQUIRE, "agent");
;             xb_add(&bar[XB_XGEN(b.x)], 1u);
;             asm volatile("s_waitcnt vmcnt(0)" ::: "memory");
;         } else {
;             XB_SPIN(xb_ld(&bar[XB_XGEN(b.x)]) == gen, bar);
;             __builtin_amdgcn_fence(__ATOMIC_ACQUIRE, "agent");
;             asm volatile("s_waitcnt vmcnt(0)" ::: "memory");
.LBB0_1077:
	s_or_b64 exec, exec, s[10:11]
	v_cvt_f32_u32_e32 v5, v3
	s_waitcnt vmcnt(0)
	v_readfirstlane_b32 s4, v4
	v_sub_u32_e32 v4, 0, v3
	v_rcp_iflag_f32_e32 v5, v5
	v_add_u32_e32 v6, s4, v1
	v_mul_f32_e32 v5, 0x4f7ffffe, v5
	v_cvt_u32_f32_e32 v5, v5
	v_mul_lo_u32 v1, v4, v5
	v_mul_hi_u32 v1, v5, v1
	v_add_u32_e32 v1, v5, v1
	v_mul_hi_u32 v1, v6, v1
	v_mul_lo_u32 v4, v1, v3
	v_sub_u32_e32 v4, v6, v4
	v_add_u32_e32 v5, 1, v1
	v_cmp_ge_u32_e32 vcc, v4, v3
	s_nop 1
	v_cndmask_b32_e32 v1, v1, v5, vcc
	v_sub_u32_e32 v5, v4, v3
	v_cndmask_b32_e32 v4, v4, v5, vcc
	v_add_u32_e32 v5, 1, v1
	v_cmp_ge_u32_e32 vcc, v4, v3
	v_add_u32_e32 v4, 1, v6
	s_nop 0
	v_cndmask_b32_e32 v1, v1, v5, vcc
	v_mul_lo_u32 v5, v3, v1
	v_add_u32_e32 v3, v5, v3
	v_cmp_ne_u32_e32 vcc, v4, v3
	s_and_saveexec_b64 s[10:11], vcc
	s_xor_b64 s[10:11], exec, s[10:11]
	s_cbranch_execz .LBB0_1091
	buffer_inv sc1
	v_mov_b32_e32 v4, 0x26a38
	ds_read_b32 v4, v4
	s_waitcnt lgkmcnt(0)
	v_cmp_ne_u32_e32 vcc, 0, v4
	s_cbranch_vccz .Lnl_full_5
	v_readlane_b32 s14, v253, 34
	v_readlane_b32 s15, v253, 35
	s_mov_b32 s4, 0
	s_nop 3
.Lnl_lspin_5:
	global_load_dword v2, v99, s[14:15] sc1
	s_waitcnt vmcnt(0)
	v_cmp_lt_u32_e32 vcc, v2, v3
	s_cbranch_vccz .Lnl_acq_5
	s_sleep 1
	s_add_i32 s4, s4, 1
	s_cmp_lt_u32 s4, 0x40000
	s_cbranch_scc1 .Lnl_lspin_5
	s_branch .Lnl_acq_5
.Lnl_full_5:
	v_mov_b32_e32 v4, 0x26a48
	ds_read_b32 v4, v4
	v_readlane_b32 s14, v253, 40
	v_readlane_b32 s15, v253, 41
	s_mov_b32 s4, 0
	s_waitcnt lgkmcnt(0)
	s_nop 2
.Lnl_fspin_5:
	global_load_dword v2, v99, s[14:15] sc1
	s_waitcnt vmcnt(0)
	v_cmp_lt_u32_e32 vcc, v2, v4
	s_cbranch_vccz .Lnl_acq_5
	s_sleep 1
	s_add_i32 s4, s4, 1
	s_cmp_lt_u32 s4, 0x40000
	s_cbranch_scc1 .Lnl_fspin_5
	s_branch .Lnl_acq_5
	v_readlane_b32 s14, v253, 36
	v_readlane_b32 s15, v253, 37
	s_waitcnt lgkmcnt(0)
	s_nop 3
	global_load_dword v2, v99, s[14:15] sc1
	s_waitcnt vmcnt(0)
	v_cmp_eq_u32_e32 vcc, v2, v1
	s_and_saveexec_b64 s[14:15], vcc
	s_cbranch_execz .LBB0_1090
	s_mov_b32 s4, 1
	s_mov_b64 s[34:35], 0
	s_branch .LBB0_1081

; __device__ __forceinline__ unsigned xb_add(unsigned* p, unsigned v) { return __hip_atomic_fetch_add(p, v, __ATOMIC_RELAXED, __HIP_MEMORY_SCOPE_AGENT); }
; __device__ __forceinline__ void xcd_barrier(const XcdBarrier& b) {
;     asm volatile("s_waitcnt vmcnt(0)" ::: "memory");
;     __syncthreads();
;     if (threadIdx.x == 0) {
;         unsigned* bar = b.bar;
;         __builtin_amdgcn_s_waitcnt(0);
;         unsigned nloc = b.st[0], nx = b.st[1];
;         if (nloc == 0u) { xcd_barrier_complete(bar, b.x, nloc, nx); b.st[0] = nloc; b.st[1] = nx; }
;         const unsigned old = xb_add(&bar[XB_XSUB(b.x)], 1u);
.LBB0_1216:
	s_waitcnt vmcnt(0)
	s_waitcnt lgkmcnt(0)
	s_barrier
	s_mov_b64 s[2:3], exec
	v_readlane_b32 s6, v252, 10
	v_readlane_b32 s7, v252, 11
	s_and_b64 s[6:7], s[2:3], s[6:7]
	s_mov_b64 exec, s[6:7]
	s_cbranch_execz .LBB0_1268
	v_mov_b32_e32 v4, 0x26a48
	ds_read_b32 v5, v4
	s_waitcnt lgkmcnt(0)
	v_add_u32_e32 v5, 1, v5
	ds_write_b32 v4, v5
	v_readlane_b32 s1, v255, 21
	s_waitcnt vmcnt(0) expcnt(0) lgkmcnt(0)
	s_nop 0
	v_mov_b32_e32 v1, s1
	ds_read_b32 v3, v1
	v_readlane_b32 s1, v255, 22
	s_waitcnt lgkmcnt(0)
	v_cmp_ne_u32_e32 vcc, 0, v3
	v_mov_b32_e32 v1, s1
	ds_read_b32 v2, v1
	s_cbranch_vccnz .LBB0_1232
	s_mov_b32 s4, 1
	s_branch .LBB0_1220

; __device__ __forceinline__ unsigned xb_ld(unsigned* p)              { return __hip_atomic_load(p, __ATOMIC_RELAXED, __HIP_MEMORY_SCOPE_AGENT); }
; __device__ __forceinline__ unsigned xb_add(unsigned* p, unsigned v) { return __hip_atomic_fetch_add(p, v, __ATOMIC_RELAXED, __HIP_MEMORY_SCOPE_AGENT); }
; #define XB_SPIN(cond, bar) do { unsigned _sp = 0; while (cond) { __builtin_amdgcn_s_sleep(1); \
;     if ((++_sp & 255u) == 0u) { if (xb_ld(&(bar)[XB_TMO])) break; if (_sp > XB_SPIN_CAP) { atomicAdd(&(bar)[XB_TMO], 1u); break; } } } } while (0)
; __device__ __forceinline__ void xcd_barrier(const XcdBarrier& b) {
;     ...
;         const unsigned old = xb_add(&bar[XB_XSUB(b.x)], 1u);
;         const unsigned gen = old / nloc;
;         if (old + 1u == (gen + 1u) * nloc) {
;             __builtin_amdgcn_fence(__ATOMIC_RELEASE, "agent");
;             asm volatile("s_waitcnt vmcnt(0)" ::: "memory");
;             const unsigned og = xb_add(&bar[XB_TOP], 1u);
;             const unsigned tg = og / nx;
;             if (og + 1u == (tg + 1u) * nx) xb_add(&bar[XB_TOPGEN], 1u);
;             else XB_SPIN(xb_ld(&bar[XB_TOPGEN]) == tg, bar);
;             __builtin_amdgcn_fence(__ATOMIC_ACQUIRE, "agent");
;             xb_add(&bar[XB_XGEN(b.x)], 1u);
;             asm volatile("s_waitcnt vmcnt(0)" ::: "memory");
;         } else {
;             XB_SPIN(xb_ld(&bar[XB_XGEN(b.x)]) == gen, bar);
;             __builtin_amdgcn_fence(__ATOMIC_ACQUIRE, "agent");
;             asm volatile("s_waitcnt vmcnt(0)" ::: "memory");
.LBB0_1234:
	s_or_b64 exec, exec, s[6:7]
	v_cvt_f32_u32_e32 v5, v3
	s_waitcnt vmcnt(0)
	v_readfirstlane_b32 s4, v4
	v_sub_u32_e32 v4, 0, v3
	v_rcp_iflag_f32_e32 v5, v5
	v_add_u32_e32 v6, s4, v1
	v_mul_f32_e32 v5, 0x4f7ffffe, v5
	v_cvt_u32_f32_e32 v5, v5
	v_mul_lo_u32 v1, v4, v5
	v_mul_hi_u32 v1, v5, v1
	v_add_u32_e32 v1, v5, v1
	v_mul_hi_u32 v1, v6, v1
	v_mul_lo_u32 v4, v1, v3
	v_sub_u32_e32 v4, v6, v4
	v_add_u32_e32 v5, 1, v1
	v_cmp_ge_u32_e32 vcc, v4, v3
	s_nop 1
	v_cndmask_b32_e32 v1, v1, v5, vcc
	v_sub_u32_e32 v5, v4, v3
	v_cndmask_b32_e32 v4, v4, v5, vcc
	v_add_u32_e32 v5, 1, v1
	v_cmp_ge_u32_e32 vcc, v4, v3
	v_add_u32_e32 v4, 1, v6
	s_nop 0
	v_cndmask_b32_e32 v1, v1, v5, vcc
	v_mul_lo_u32 v5, v3, v1
	v_add_u32_e32 v3, v5, v3
	v_cmp_ne_u32_e32 vcc, v4, v3
	s_and_saveexec_b64 s[6:7], vcc
	s_xor_b64 s[6:7], exec, s[6:7]
	s_cbranch_execz .LBB0_1248
	buffer_inv sc1
	v_mov_b32_e32 v4, 0x26a48
	ds_read_b32 v4, v4
	v_readlane_b32 s8, v253, 40
	v_readlane_b32 s9, v253, 41
	s_mov_b32 s4, 0
	s_waitcnt lgkmcnt(0)
	s_nop 2

; __device__ __forceinline__ unsigned xb_add(unsigned* p, unsigned v) { return __hip_atomic_fetch_add(p, v, __ATOMIC_RELAXED, __HIP_MEMORY_SCOPE_AGENT); }
; __device__ __forceinline__ void xcd_barrier(const XcdBarrier& b) {
;     asm volatile("s_waitcnt vmcnt(0)" ::: "memory");
;     __syncthreads();
;     if (threadIdx.x == 0) {
;         unsigned* bar = b.bar;
;         __builtin_amdgcn_s_waitcnt(0);
;         unsigned nloc = b.st[0], nx = b.st[1];
;         if (nloc == 0u) { xcd_barrier_complete(bar, b.x, nloc, nx); b.st[0] = nloc; b.st[1] = nx; }
;         const unsigned old = xb_add(&bar[XB_XSUB(b.x)], 1u);
.LBB0_1320:
	s_waitcnt vmcnt(0)
	s_barrier
	s_mov_b64 s[2:3], exec
	v_readlane_b32 s6, v252, 10
	v_readlane_b32 s7, v252, 11
	s_and_b64 s[6:7], s[2:3], s[6:7]
	s_mov_b64 exec, s[6:7]
	s_cbranch_execz .LBB0_1372
	v_mov_b32_e32 v4, 0x26a48
	ds_read_b32 v5, v4
	s_waitcnt lgkmcnt(0)
	v_add_u32_e32 v5, 1, v5
	ds_write_b32 v4, v5
	v_readlane_b32 s1, v255, 21
	s_waitcnt vmcnt(0) expcnt(0) lgkmcnt(0)
	s_nop 0
	v_mov_b32_e32 v1, s1
	ds_read_b32 v3, v1
	v_readlane_b32 s1, v255, 22
	s_waitcnt lgkmcnt(0)
	v_cmp_ne_u32_e32 vcc, 0, v3
	v_mov_b32_e32 v1, s1
	ds_read_b32 v2, v1
	s_cbranch_vccnz .LBB0_1336
	s_mov_b32 s4, 1
	s_branch .LBB0_1324

; __device__ __forceinline__ unsigned xb_add(unsigned* p, unsigned v) { return __hip_atomic_fetch_add(p, v, __ATOMIC_RELAXED, __HIP_MEMORY_SCOPE_AGENT); }
; __device__ __forceinline__ void xcd_barrier(const XcdBarrier& b) {
;     asm volatile("s_waitcnt vmcnt(0)" ::: "memory");
;     __syncthreads();
;     if (threadIdx.x == 0) {
;         unsigned* bar = b.bar;
;         __builtin_amdgcn_s_waitcnt(0);
;         unsigned nloc = b.st[0], nx = b.st[1];
;         if (nloc == 0u) { xcd_barrier_complete(bar, b.x, nloc, nx); b.st[0] = nloc; b.st[1] = nx; }
;         const unsigned old = xb_add(&bar[XB_XSUB(b.x)], 1u);
.LBB0_1417:
	s_waitcnt vmcnt(0)
	s_waitcnt lgkmcnt(0)
	s_barrier
	s_mov_b64 s[2:3], exec
	v_readlane_b32 s6, v252, 10
	v_readlane_b32 s7, v252, 11
	s_and_b64 s[6:7], s[2:3], s[6:7]
	v_readlane_b32 s80, v255, 36
	v_readlane_b32 s81, v255, 37
	s_mov_b64 exec, s[6:7]
	s_cbranch_execz .LBB0_1469
	v_mov_b32_e32 v4, 0x26a38
	ds_read_b32 v5, v4
	ds_read_b32 v6, v4 offset:16
	s_waitcnt lgkmcnt(0)
	v_cmp_eq_u32_e32 vcc, 0, v5
	s_nop 1
	v_cndmask_b32_e64 v5, 0, 1, vcc
	v_add_u32_e32 v6, v6, v5
	ds_write_b32 v4, v6 offset:16
	v_mov_b32_e32 v4, 0x26a24
	ds_read_b32 v5, v4
	ds_read_b32 v6, v4 offset:32
	s_waitcnt lgkmcnt(0)
	v_add_u32_e32 v5, v6, v5
	ds_write_b32 v4, v5 offset:32
	v_readlane_b32 s1, v255, 21
	s_waitcnt vmcnt(0) expcnt(0) lgkmcnt(0)
	s_nop 0
	v_mov_b32_e32 v1, s1
	ds_read_b32 v3, v1
	v_readlane_b32 s1, v255, 22
	s_waitcnt lgkmcnt(0)
	v_cmp_ne_u32_e32 vcc, 0, v3
	v_mov_b32_e32 v1, s1
	ds_read_b32 v2, v1
	s_cbranch_vccnz .LBB0_1433
	s_mov_b32 s4, 1
	s_branch .LBB0_1421

; __device__ __forceinline__ unsigned xb_add(unsigned* p, unsigned v) { return __hip_atomic_fetch_add(p, v, __ATOMIC_RELAXED, __HIP_MEMORY_SCOPE_AGENT); }
; __device__ __forceinline__ void xcd_barrier(const XcdBarrier& b) {
;     asm volatile("s_waitcnt vmcnt(0)" ::: "memory");
;     __syncthreads();
;     if (threadIdx.x == 0) {
;         unsigned* bar = b.bar;
;         __builtin_amdgcn_s_waitcnt(0);
;         unsigned nloc = b.st[0], nx = b.st[1];
;         if (nloc == 0u) { xcd_barrier_complete(bar, b.x, nloc, nx); b.st[0] = nloc; b.st[1] = nx; }
;         const unsigned old = xb_add(&bar[XB_XSUB(b.x)], 1u);
.LBB0_1694:
	s_waitcnt vmcnt(0)
	s_waitcnt lgkmcnt(0)
	s_barrier
	s_mov_b64 s[2:3], exec
	v_readlane_b32 s6, v252, 10
	v_readlane_b32 s7, v252, 11
	s_and_b64 s[6:7], s[2:3], s[6:7]
	s_mov_b64 exec, s[6:7]
	s_cbranch_execz .LBB0_1746
	v_mov_b32_e32 v4, 0x26a38
	ds_read_b32 v5, v4
	ds_read_b32 v6, v4 offset:16
	s_waitcnt lgkmcnt(0)
	v_cmp_eq_u32_e32 vcc, 0, v5
	s_nop 1
	v_cndmask_b32_e64 v5, 0, 1, vcc
	v_add_u32_e32 v6, v6, v5
	ds_write_b32 v4, v6 offset:16
	v_readlane_b32 s1, v255, 21
	s_waitcnt vmcnt(0) expcnt(0) lgkmcnt(0)
	s_nop 0
	v_mov_b32_e32 v1, s1
	ds_read_b32 v3, v1
	v_readlane_b32 s1, v255, 22
	s_waitcnt lgkmcnt(0)
	v_cmp_ne_u32_e32 vcc, 0, v3
	v_mov_b32_e32 v1, s1
	ds_read_b32 v2, v1
	s_cbranch_vccnz .LBB0_1710
	s_mov_b32 s4, 1
	s_branch .LBB0_1698

; __device__ __forceinline__ unsigned xb_add(unsigned* p, unsigned v) { return __hip_atomic_fetch_add(p, v, __ATOMIC_RELAXED, __HIP_MEMORY_SCOPE_AGENT); }
; __device__ __forceinline__ void xcd_barrier(const XcdBarrier& b) {
;     asm volatile("s_waitcnt vmcnt(0)" ::: "memory");
;     __syncthreads();
;     if (threadIdx.x == 0) {
;         unsigned* bar = b.bar;
;         __builtin_amdgcn_s_waitcnt(0);
;         unsigned nloc = b.st[0], nx = b.st[1];
;         if (nloc == 0u) { xcd_barrier_complete(bar, b.x, nloc, nx); b.st[0] = nloc; b.st[1] = nx; }
;         const unsigned old = xb_add(&bar[XB_XSUB(b.x)], 1u);
.LBB0_1877:
	v_mov_b32_e32 v4, 0x26a48
	ds_read_b32 v5, v4
	s_waitcnt lgkmcnt(0)
	v_add_u32_e32 v5, 1, v5
	ds_write_b32 v4, v5
	v_readlane_b32 s1, v255, 21
	s_waitcnt vmcnt(0) expcnt(0) lgkmcnt(0)
	s_nop 0
	v_mov_b32_e32 v1, s1
	ds_read_b32 v3, v1
	v_readlane_b32 s1, v255, 22
	s_waitcnt lgkmcnt(0)
	v_cmp_ne_u32_e32 vcc, 0, v3
	v_mov_b32_e32 v1, s1
	ds_read_b32 v2, v1
	s_cbranch_vccnz .LBB0_1892
	s_mov_b32 s4, 1
	s_branch .LBB0_1880
